# v76 + O4 attention output rows staged through LDS and stored as 16-byte row chunks
# baseline (speedup 1.0000x reference)
.LBB0_572:
	v_add_f32_e32 v32, v32, v33
	v_div_scale_f32 v33, s[2:3], v32, v32, 1.0
	v_rcp_f32_e32 v34, v33
	v_div_scale_f32 v35, vcc, 1.0, v32, 1.0
	v_lshlrev_b32_e32 v128, 3, v150
	v_fma_f32 v36, -v33, v34, 1.0
	v_fmac_f32_e32 v34, v36, v34
	v_mul_f32_e32 v36, v35, v34
	v_fma_f32 v37, -v33, v36, v35
	v_fmac_f32_e32 v36, v37, v34
	v_fma_f32 v33, -v33, v36, v35
	v_div_fmas_f32 v33, v33, v34, v36
	v_div_fixup_f32 v34, v33, v32, 1.0
	v_lshlrev_b64 v[32:33], 11, v[134:135]
	v_lshl_add_u64 v[32:33], s[0:1], 0, v[32:33]
	v_mul_f32_e32 v16, v16, v34
	v_mul_f32_e32 v17, v17, v34
	v_mul_f32_e32 v18, v18, v34
	v_mul_f32_e32 v19, v19, v34
	v_mul_f32_e32 v0, v0, v34
	v_mul_f32_e32 v1, v1, v34
	v_mul_f32_e32 v2, v2, v34
	v_mul_f32_e32 v3, v3, v34
	v_lshl_add_u64 v[32:33], v[32:33], 0, v[128:129]
	v_cvt_pk_bf16_f32 v16, v16, v17
	v_cvt_pk_bf16_f32 v17, v18, v19
	v_cvt_pk_bf16_f32 v0, v0, v1
	v_cvt_pk_bf16_f32 v1, v2, v3
	v_and_b32_e32 v240, 31, v155
	v_bfe_u32 v246, v155, 3, 3
	v_lshrrev_b32_e32 v239, 6, v155
	v_mul_u32_u24_e32 v239, 0x1400, v239
	v_add_u32_e32 v239, 0x10000, v239
	v_mul_u32_u24_e32 v238, 0x90, v240
	v_mul_u32_u24_e32 v247, 0x90, v246
	v_add_u32_e32 v238, v238, v239
	v_add_u32_e32 v239, v247, v239
	v_sub_u32_e32 v247, v246, v240
	v_lshlrev_b32_e32 v247, 11, v247
	v_and_b32_e32 v246, 7, v155
	v_lshl_add_u32 v239, v246, 4, v239
	v_lshl_add_u32 v247, v246, 4, v247
	v_bfe_u32 v246, v155, 5, 1
	v_lshl_add_u32 v238, v246, 3, v238
	v_lshlrev_b32_e32 v246, 3, v246
	v_sub_u32_e32 v246, v247, v246
	v_ashrrev_i32_e32 v247, 31, v246
	v_lshl_add_u64 v[244:245], v[32:33], 0, v[246:247]
	v_mov_b32_e32 v246, 0x4000
	v_mov_b32_e32 v247, 0
	ds_write_b64 v238, v[16:17]
	v_mul_f32_e32 v16, v20, v34
	v_mul_f32_e32 v17, v21, v34
	v_mul_f32_e32 v18, v22, v34
	v_mul_f32_e32 v19, v23, v34
	ds_write_b64 v238, v[0:1] offset:64
	v_mul_f32_e32 v0, v4, v34
	v_mul_f32_e32 v1, v5, v34
	v_mul_f32_e32 v2, v6, v34
	v_mul_f32_e32 v3, v7, v34
	v_cvt_pk_bf16_f32 v16, v16, v17
	v_cvt_pk_bf16_f32 v17, v18, v19
	v_cvt_pk_bf16_f32 v0, v0, v1
	v_cvt_pk_bf16_f32 v1, v2, v3
	ds_write_b64 v238, v[16:17] offset:16
	v_mul_f32_e32 v16, v24, v34
	v_mul_f32_e32 v17, v25, v34
	v_mul_f32_e32 v18, v26, v34
	v_mul_f32_e32 v19, v27, v34
	ds_write_b64 v238, v[0:1] offset:80
	v_mul_f32_e32 v0, v8, v34
	v_mul_f32_e32 v1, v9, v34
	v_mul_f32_e32 v2, v10, v34
	v_mul_f32_e32 v3, v11, v34
	v_cvt_pk_bf16_f32 v16, v16, v17
	v_cvt_pk_bf16_f32 v17, v18, v19
	v_cvt_pk_bf16_f32 v0, v0, v1
	v_cvt_pk_bf16_f32 v1, v2, v3
	ds_write_b64 v238, v[16:17] offset:32
	v_mul_f32_e32 v16, v28, v34
	v_mul_f32_e32 v17, v29, v34
	v_mul_f32_e32 v18, v30, v34
	v_mul_f32_e32 v19, v31, v34
	ds_write_b64 v238, v[0:1] offset:96
	v_mul_f32_e32 v0, v12, v34
	v_mul_f32_e32 v1, v13, v34
	v_mul_f32_e32 v2, v14, v34
	v_mul_f32_e32 v3, v15, v34
	s_add_i32 s30, s30, s38
	s_add_i32 s52, s52, s38
	v_cvt_pk_bf16_f32 v16, v16, v17
	v_cvt_pk_bf16_f32 v17, v18, v19
	v_cvt_pk_bf16_f32 v0, v0, v1
	v_cvt_pk_bf16_f32 v1, v2, v3
	s_cmpk_gt_i32 s30, 0x17f
	ds_write_b64 v238, v[16:17] offset:48
	ds_write_b64 v238, v[0:1] offset:112
	s_waitcnt lgkmcnt(0)
	ds_read_b128 v[230:233], v239 offset:0
	ds_read_b128 v[234:237], v239 offset:1152
	ds_read_b128 v[196:199], v239 offset:2304
	ds_read_b128 v[200:203], v239 offset:3456
	s_waitcnt lgkmcnt(3)
	global_store_dwordx4 v[244:245], v[230:233], off
	v_lshl_add_u64 v[244:245], v[244:245], 0, v[246:247]
	s_waitcnt lgkmcnt(2)
	global_store_dwordx4 v[244:245], v[234:237], off
	v_lshl_add_u64 v[244:245], v[244:245], 0, v[246:247]
	s_waitcnt lgkmcnt(1)
	global_store_dwordx4 v[244:245], v[196:199], off
	v_lshl_add_u64 v[244:245], v[244:245], 0, v[246:247]
	s_waitcnt lgkmcnt(0)
	global_store_dwordx4 v[244:245], v[200:203], off
	s_cbranch_scc1 .LBB0_626
